# seam-1 grid barrier moved to after the 5th in-projection unit (6th-round units run beside attention)
# baseline (speedup 1.0000x reference)
.LBB0_124:
	s_mov_b32 s100, 0
	v_mov_b32_e32 v14, v0
	s_cmp_gt_i32 s95, -1
	v_readfirstlane_b32 s2, v14
	s_cbranch_scc0 .LBB0_126
	s_lshl_b32 s4, s95, 7
	s_cbranch_execz .LBB0_127
	s_branch .LBB0_128

.LBB0_246:
	s_add_i32 s100, s100, 1
	s_cmp_lg_u32 s100, 5
	s_cbranch_scc1 .Lsm1_skip
	v_mov_b32_e32 v101, v1
	v_writelane_b32 v100, s0, 0
	v_writelane_b32 v100, s1, 1
	v_writelane_b32 v100, s2, 2
	v_writelane_b32 v100, s3, 3
	v_writelane_b32 v100, s4, 4
	v_writelane_b32 v100, s5, 5
	v_writelane_b32 v100, s6, 6
	v_writelane_b32 v100, s7, 7
	v_writelane_b32 v100, s8, 8
	v_writelane_b32 v100, s9, 9
	v_writelane_b32 v100, s10, 10
	v_writelane_b32 v100, s11, 11
	v_writelane_b32 v100, s12, 12
	v_writelane_b32 v100, s13, 13
	v_writelane_b32 v100, s14, 14
	v_writelane_b32 v100, s15, 15
	v_writelane_b32 v100, s16, 16
	v_writelane_b32 v100, s17, 17
	v_writelane_b32 v100, s18, 18
	v_writelane_b32 v100, s19, 19
	v_writelane_b32 v100, s20, 20
	v_writelane_b32 v100, s21, 21
	v_writelane_b32 v100, s22, 22
	v_writelane_b32 v100, s23, 23
	v_writelane_b32 v100, s24, 24
	v_writelane_b32 v100, s25, 25
	v_writelane_b32 v100, s26, 26
	v_writelane_b32 v100, s27, 27
	v_writelane_b32 v100, s28, 28
	v_writelane_b32 v100, s29, 29
	v_writelane_b32 v100, s30, 30
	v_writelane_b32 v100, s31, 31
	v_writelane_b32 v100, s33, 32
	v_writelane_b32 v100, s34, 33
	v_writelane_b32 v100, s35, 34
	v_writelane_b32 v100, s36, 35
	v_writelane_b32 v100, s37, 36
	v_writelane_b32 v100, s38, 37
	v_writelane_b32 v100, s39, 38
	v_writelane_b32 v100, s40, 39
	v_writelane_b32 v100, s41, 40
	v_writelane_b32 v100, s42, 41
	v_writelane_b32 v100, s43, 42
	v_writelane_b32 v100, s44, 43
	v_writelane_b32 v100, s45, 44
	v_writelane_b32 v100, s48, 45
	v_writelane_b32 v100, s49, 46
	v_writelane_b32 v100, s82, 47
	v_writelane_b32 v100, s83, 48
	v_writelane_b32 v100, s94, 49
	v_writelane_b32 v100, s95, 50
	v_writelane_b32 v100, s96, 51
	v_writelane_b32 v100, s97, 52
	v_readlane_b32 s96, v254, 26
	v_readlane_b32 s97, v254, 27
	s_waitcnt vmcnt(0) lgkmcnt(0)
	s_barrier
	s_and_saveexec_b64 s[0:1], s[96:97]
	s_cbranch_execz .Lsm1_252
	s_mov_b64 s[2:3], exec
	v_mbcnt_lo_u32_b32 v1, s2, 0
	v_mbcnt_hi_u32_b32 v1, s3, v1
	v_cmp_eq_u32_e32 vcc, 0, v1
	s_and_b64 s[4:5], exec, vcc
	s_mov_b64 exec, s[4:5]
	s_cbranch_execz .Lsm1_252
	s_bcnt1_i32_b64 s2, s[2:3]
	v_mov_b32_e32 v1, 0xf000
	v_mov_b32_e32 v2, s2
	global_atomic_add v1, v2, s[72:73] offset:768

.Lsm1_304:
	s_or_b64 exec, exec, s[0:1]
	s_waitcnt lgkmcnt(0)
	s_barrier
	v_readlane_b32 s0, v100, 0
	v_readlane_b32 s1, v100, 1
	v_readlane_b32 s2, v100, 2
	v_readlane_b32 s3, v100, 3
	v_readlane_b32 s4, v100, 4
	v_readlane_b32 s5, v100, 5
	v_readlane_b32 s6, v100, 6
	v_readlane_b32 s7, v100, 7
	v_readlane_b32 s8, v100, 8
	v_readlane_b32 s9, v100, 9
	v_readlane_b32 s10, v100, 10
	v_readlane_b32 s11, v100, 11
	v_readlane_b32 s12, v100, 12
	v_readlane_b32 s13, v100, 13
	v_readlane_b32 s14, v100, 14
	v_readlane_b32 s15, v100, 15
	v_readlane_b32 s16, v100, 16
	v_readlane_b32 s17, v100, 17
	v_readlane_b32 s18, v100, 18
	v_readlane_b32 s19, v100, 19
	v_readlane_b32 s20, v100, 20
	v_readlane_b32 s21, v100, 21
	v_readlane_b32 s22, v100, 22
	v_readlane_b32 s23, v100, 23
	v_readlane_b32 s24, v100, 24
	v_readlane_b32 s25, v100, 25
	v_readlane_b32 s26, v100, 26
	v_readlane_b32 s27, v100, 27
	v_readlane_b32 s28, v100, 28
	v_readlane_b32 s29, v100, 29
	v_readlane_b32 s30, v100, 30
	v_readlane_b32 s31, v100, 31
	v_readlane_b32 s33, v100, 32
	v_readlane_b32 s34, v100, 33
	v_readlane_b32 s35, v100, 34
	v_readlane_b32 s36, v100, 35
	v_readlane_b32 s37, v100, 36
	v_readlane_b32 s38, v100, 37
	v_readlane_b32 s39, v100, 38
	v_readlane_b32 s40, v100, 39
	v_readlane_b32 s41, v100, 40
	v_readlane_b32 s42, v100, 41
	v_readlane_b32 s43, v100, 42
	v_readlane_b32 s44, v100, 43
	v_readlane_b32 s45, v100, 44
	v_readlane_b32 s48, v100, 45
	v_readlane_b32 s49, v100, 46
	v_readlane_b32 s82, v100, 47
	v_readlane_b32 s83, v100, 48
	v_readlane_b32 s94, v100, 49
	v_readlane_b32 s95, v100, 50
	v_readlane_b32 s96, v100, 51
	v_readlane_b32 s97, v100, 52
	v_mov_b32_e32 v1, v101
	s_nop 4

.LBB0_249:
	s_waitcnt vmcnt(0)
	s_barrier
	s_waitcnt vmcnt(0)
	v_readlane_b32 s96, v254, 26
	v_readlane_b32 s97, v254, 27
	s_waitcnt vmcnt(0) lgkmcnt(0)
	v_readlane_b32 s82, v254, 31
	v_readlane_b32 s94, v254, 29
	v_readlane_b32 s95, v254, 28
	v_readlane_b32 s83, v254, 32
	v_mov_b32_e32 v183, v0
	s_add_u32 s12, s72, 0xeb00
	s_waitcnt lgkmcnt(0)
	s_barrier
	s_addc_u32 s13, s73, 0
	v_cmp_eq_u32_e64 s[2:3], 0, v183
	s_and_saveexec_b64 s[0:1], s[2:3]
	s_cbranch_execz .LBB0_310
	s_mov_b64 s[6:7], exec
	v_mbcnt_lo_u32_b32 v1, s6, 0
	v_mbcnt_hi_u32_b32 v1, s7, v1
	v_cmp_eq_u32_e32 vcc, 0, v1
	s_and_saveexec_b64 s[4:5], vcc
	s_cbranch_execz .LBB0_307
	s_bcnt1_i32_b64 s6, s[6:7]
	v_mov_b32_e32 v2, 0
	v_mov_b32_e32 v3, s6
	global_atomic_add v2, v2, v3, s[12:13] sc0
